# stack + FFN-up unit start without the compiler's vmcnt(0) drain
# baseline (speedup 1.0000x reference)
.LBB0_166:
	s_ashr_i32 s27, s26, 31
	s_lshl_b64 s[28:29], s[26:27], 19
	s_add_u32 s28, s69, s28
	s_addc_u32 s29, s78, s29
	s_and_b64 s[30:31], s[4:5], exec
	s_cselect_b32 s2, s29, s39
	s_cselect_b32 s15, s28, s38
	s_ashr_i32 s25, s24, 31
	s_lshl_b64 s[30:31], s[24:25], 19
	s_add_u32 s30, s7, s30
	s_addc_u32 s31, s79, s31
	s_and_b64 s[42:43], s[4:5], exec
	s_cselect_b32 s25, s31, s63
	s_cselect_b32 s27, s30, s62
	s_add_u32 s38, s38, 0x40080
	s_addc_u32 s39, s39, 0
	s_add_u32 s35, s62, 0x100
	s_addc_u32 s42, s63, 0
	s_mov_b32 s43, -2
	s_add_u32 s48, s38, 0xfffc0080
	s_addc_u32 s49, s39, -1
	s_add_i32 s59, 0, 0x10000
	s_cmp_eq_u32 s43, 12
	s_cselect_b32 s65, s2, s49
	s_cselect_b32 s64, s15, s48
	v_add_u32_e32 v142, s59, v145
	s_cselect_b32 s63, s25, s42
	s_cselect_b32 s62, s27, s35
	s_add_i32 s66, 0, 0x14000
	ds_read_b128 v[148:151], v142
	ds_read_b128 v[152:155], v142 offset:1024
	ds_read_b128 v[156:159], v142 offset:2048
	ds_read_b128 v[160:163], v142 offset:3072
	v_add_u32_e32 v142, s66, v145
	ds_read_b128 v[164:167], v142
	ds_read_b128 v[168:171], v142 offset:1024
	ds_read_b128 v[172:175], v142 offset:2048
	ds_read_b128 v[180:183], v142 offset:3072
	v_lshl_add_u64 v[142:143], s[38:39], 0, v[136:137]
	s_add_i32 m0, s37, 0xc000
	ds_read_b128 v[184:187], v147
	ds_read_b128 v[188:191], v147 offset:1024
	ds_read_b128 v[192:195], v147 offset:2048
	ds_read_b128 v[196:199], v147 offset:3072
	ds_read_b128 v[200:203], v147 offset:4096
	ds_read_b128 v[204:207], v147 offset:5120
	ds_read_b128 v[208:211], v147 offset:6144
	ds_read_b128 v[212:215], v147 offset:7168
	global_load_lds_dwordx4 v[142:143], off
	v_lshl_add_u64 v[142:143], s[38:39], 0, v[138:139]
	s_add_i32 m0, s37, 0xe000
	s_nop 0
	global_load_lds_dwordx4 v[142:143], off
	s_waitcnt vmcnt(8)
	s_waitcnt lgkmcnt(0)
	s_barrier
	s_setprio 1
	s_waitcnt lgkmcnt(0)
	v_mfma_f32_16x16x32_bf16 v[126:129], v[148:151], v[184:187], 0
	v_mfma_f32_16x16x32_bf16 v[118:121], v[156:159], v[184:187], 0
	v_mfma_f32_16x16x32_bf16 v[110:113], v[148:151], v[192:195], 0
	v_mfma_f32_16x16x32_bf16 v[102:105], v[156:159], v[192:195], 0
	v_mfma_f32_16x16x32_bf16 v[94:97], v[148:151], v[200:203], 0
	v_mfma_f32_16x16x32_bf16 v[86:89], v[156:159], v[200:203], 0
	v_mfma_f32_16x16x32_bf16 v[78:81], v[148:151], v[208:211], 0
	v_mfma_f32_16x16x32_bf16 v[70:73], v[156:159], v[208:211], 0
	v_mfma_f32_16x16x32_bf16 v[126:129], v[152:155], v[188:191], v[126:129]
	v_mfma_f32_16x16x32_bf16 v[118:121], v[160:163], v[188:191], v[118:121]
	v_mfma_f32_16x16x32_bf16 v[110:113], v[152:155], v[196:199], v[110:113]
	v_mfma_f32_16x16x32_bf16 v[102:105], v[160:163], v[196:199], v[102:105]
	v_mfma_f32_16x16x32_bf16 v[94:97], v[152:155], v[204:207], v[94:97]
	v_mfma_f32_16x16x32_bf16 v[86:89], v[160:163], v[204:207], v[86:89]
	v_mfma_f32_16x16x32_bf16 v[78:81], v[152:155], v[212:215], v[78:81]
	v_mfma_f32_16x16x32_bf16 v[70:73], v[160:163], v[212:215], v[70:73]
	s_setprio 0
	s_setprio 1
	v_mfma_f32_16x16x32_bf16 v[122:125], v[164:167], v[184:187], 0
	v_mfma_f32_16x16x32_bf16 v[114:117], v[172:175], v[184:187], 0
	v_mfma_f32_16x16x32_bf16 v[106:109], v[164:167], v[192:195], 0
	v_mfma_f32_16x16x32_bf16 v[98:101], v[172:175], v[192:195], 0
	v_mfma_f32_16x16x32_bf16 v[90:93], v[164:167], v[200:203], 0
	v_mfma_f32_16x16x32_bf16 v[82:85], v[172:175], v[200:203], 0
	v_mfma_f32_16x16x32_bf16 v[74:77], v[164:167], v[208:211], 0
	v_mfma_f32_16x16x32_bf16 v[66:69], v[172:175], v[208:211], 0
	v_mfma_f32_16x16x32_bf16 v[122:125], v[168:171], v[188:191], v[122:125]
	v_mfma_f32_16x16x32_bf16 v[114:117], v[180:183], v[188:191], v[114:117]
	v_mfma_f32_16x16x32_bf16 v[106:109], v[168:171], v[196:199], v[106:109]
	v_mfma_f32_16x16x32_bf16 v[98:101], v[180:183], v[196:199], v[98:101]
	v_mfma_f32_16x16x32_bf16 v[90:93], v[168:171], v[204:207], v[90:93]
	v_mfma_f32_16x16x32_bf16 v[82:85], v[180:183], v[204:207], v[82:85]
	v_mfma_f32_16x16x32_bf16 v[74:77], v[168:171], v[212:215], v[74:77]
	v_mfma_f32_16x16x32_bf16 v[66:69], v[180:183], v[212:215], v[66:69]
	s_setprio 0
	s_barrier
	s_add_i32 s48, s59, s80
	v_lshl_add_u64 v[142:143], s[62:63], 0, v[0:1]
	s_mov_b32 m0, s48
	ds_read_b128 v[184:187], v147 offset:16384
	ds_read_b128 v[188:191], v147 offset:17408
	ds_read_b128 v[192:195], v147 offset:18432
	ds_read_b128 v[196:199], v147 offset:19456
	ds_read_b128 v[200:203], v147 offset:20480
	ds_read_b128 v[204:207], v147 offset:21504
	ds_read_b128 v[208:211], v147 offset:22528
	ds_read_b128 v[212:215], v147 offset:23552
	global_load_lds_dwordx4 v[142:143], off
	s_add_i32 m0, s48, 0x2000
	s_add_u32 s48, s62, 0x40000
	v_lshl_add_u64 v[176:177], s[62:63], 0, v[130:131]
	s_addc_u32 s49, s63, 0
	s_add_i32 s59, s66, s80
	global_load_lds_dwordx4 v[176:177], off
	v_lshl_add_u64 v[216:217], s[48:49], 0, v[0:1]
	s_mov_b32 m0, s59
	v_lshl_add_u64 v[218:219], s[64:65], 0, v[132:133]
	global_load_lds_dwordx4 v[216:217], off
	v_lshl_add_u64 v[216:217], s[48:49], 0, v[130:131]
	s_add_i32 m0, s59, 0x2000
	s_nop 0
	global_load_lds_dwordx4 v[216:217], off
	v_lshl_add_u64 v[216:217], s[64:65], 0, v[134:135]
	s_mov_b32 m0, s37
	s_nop 0
	global_load_lds_dwordx4 v[216:217], off
	s_mov_b32 m0, s81
	s_nop 0
	global_load_lds_dwordx4 v[218:219], off
	s_waitcnt vmcnt(8)
	s_waitcnt lgkmcnt(0)
	s_barrier
	s_setprio 1
	s_waitcnt lgkmcnt(0)
	v_mfma_f32_16x16x32_bf16 v[62:65], v[148:151], v[184:187], 0
	v_mfma_f32_16x16x32_bf16 v[54:57], v[156:159], v[184:187], 0
	v_mfma_f32_16x16x32_bf16 v[46:49], v[148:151], v[192:195], 0
	v_mfma_f32_16x16x32_bf16 v[38:41], v[156:159], v[192:195], 0
	v_mfma_f32_16x16x32_bf16 v[30:33], v[148:151], v[200:203], 0
	v_mfma_f32_16x16x32_bf16 v[22:25], v[156:159], v[200:203], 0
	v_mfma_f32_16x16x32_bf16 v[14:17], v[148:151], v[208:211], 0
	v_mfma_f32_16x16x32_bf16 v[6:9], v[156:159], v[208:211], 0
	v_mfma_f32_16x16x32_bf16 v[62:65], v[152:155], v[188:191], v[62:65]
	v_mfma_f32_16x16x32_bf16 v[54:57], v[160:163], v[188:191], v[54:57]
	v_mfma_f32_16x16x32_bf16 v[46:49], v[152:155], v[196:199], v[46:49]
	v_mfma_f32_16x16x32_bf16 v[38:41], v[160:163], v[196:199], v[38:41]
	v_mfma_f32_16x16x32_bf16 v[30:33], v[152:155], v[204:207], v[30:33]
	v_mfma_f32_16x16x32_bf16 v[22:25], v[160:163], v[204:207], v[22:25]
	v_mfma_f32_16x16x32_bf16 v[14:17], v[152:155], v[212:215], v[14:17]
	v_mfma_f32_16x16x32_bf16 v[6:9], v[160:163], v[212:215], v[6:9]
	s_setprio 0
	s_setprio 1
	v_mfma_f32_16x16x32_bf16 v[58:61], v[164:167], v[184:187], 0
	v_mfma_f32_16x16x32_bf16 v[50:53], v[172:175], v[184:187], 0
	v_mfma_f32_16x16x32_bf16 v[42:45], v[164:167], v[192:195], 0
	v_mfma_f32_16x16x32_bf16 v[34:37], v[172:175], v[192:195], 0
	v_mfma_f32_16x16x32_bf16 v[26:29], v[164:167], v[200:203], 0
	v_mfma_f32_16x16x32_bf16 v[18:21], v[172:175], v[200:203], 0
	v_mfma_f32_16x16x32_bf16 v[10:13], v[164:167], v[208:211], 0
	v_mfma_f32_16x16x32_bf16 v[2:5], v[172:175], v[208:211], 0
	v_mfma_f32_16x16x32_bf16 v[58:61], v[168:171], v[188:191], v[58:61]
	v_mfma_f32_16x16x32_bf16 v[50:53], v[180:183], v[188:191], v[50:53]
	v_mfma_f32_16x16x32_bf16 v[42:45], v[168:171], v[196:199], v[42:45]
	v_mfma_f32_16x16x32_bf16 v[34:37], v[180:183], v[196:199], v[34:37]
	v_mfma_f32_16x16x32_bf16 v[26:29], v[168:171], v[204:207], v[26:29]
	v_mfma_f32_16x16x32_bf16 v[18:21], v[180:183], v[204:207], v[18:21]
	v_mfma_f32_16x16x32_bf16 v[10:13], v[168:171], v[212:215], v[10:13]
	v_mfma_f32_16x16x32_bf16 v[2:5], v[180:183], v[212:215], v[2:5]
	s_setprio 0
	s_barrier
	s_branch .Lmy_mid_up
